# B1 and B2-lru queues: first item of each block is static (blockIdx), counter serves indices from 512 on
# baseline (speedup 1.0000x reference)
; DI void phase_b1(const Params& p, int layer, char*, int*) {
;   int* ctr = (int*)(p.ws + W_CTR) + layer * 4 + 0;
;   for (;;) {
;     int it = pop_block(ctr, nullptr);
;     if (it >= N_SEL + N_LRU1 + N_POOL + N_KMAX) break;
;     if (it >= N_SEL + N_LRU1 + N_POOL) { int j = it - (N_SEL + N_LRU1 + N_POOL); kmax_item(p, j >> 3, j & 7, smem); }
;     else if (it < N_SEL) {
;       if (it < 1024) { int c = 64 - (it >> 4), b = (it & 15) >> 2, sub = it & 3; select_item(p, 1, b, c, sub, smem); }
;       else if (it < 1088) { int j = it - 1024; select_item(p, 0, j >> 2, 0, j & 3, smem); }
;       else select_item(p, 1, it - 1088, 0, 0, smem);
;     } else if (it < N_SEL + N_LRU1) {
;       int j = it - N_SEL;
;       int sq = j / (NTILE_P * 8), rem = j % (NTILE_P * 8);
;       lru_tile(p, layer, 1, sq, rem >> 3, rem & 7, 0, smem);
;     } else {
;       int j = it - N_SEL - N_LRU1;
;       if (j < NB_P * NTILE_P * 4) { int sq = j / (NTILE_P * 4), rem = j % (NTILE_P * 4); pool_item(p, layer, 1, sq, rem >> 2, rem & 3, smem); }
;       else { j -= NB_P * NTILE_P * 4; pool_item(p, layer, 0, j >> 2, 0, j & 3, smem); }
;     }
;   }
.LBB0_1989:
	s_or_b64 exec, exec, s[0:1]
	s_xor_b64 s[0:1], s[8:9], -1
	v_writelane_b32 v251, s0, 43
	v_readlane_b32 s4, v249, 0
	s_waitcnt lgkmcnt(0)
	v_writelane_b32 v251, s1, 44
	s_barrier
	s_mov_b32 s2, 0
	s_ashr_i32 s3, s2, 31
	v_readlane_b32 s6, v249, 2
	v_readlane_b32 s0, v251, 41
	v_readlane_b32 s5, v249, 1
	s_add_u32 s4, s4, s2
	s_mov_b32 s6, s0
	s_addc_u32 s5, s5, s3
	s_lshl_b32 s8, s6, 2
	v_readlane_b32 s1, v251, 42
	s_mov_b32 s0, s8
	s_ashr_i32 s9, s8, 31
	v_writelane_b32 v251, s0, 45
	v_readlane_b32 s7, v249, 3
	s_nop 0
	v_writelane_b32 v251, s1, 46
	s_lshl_b64 s[0:1], s[8:9], 2
	s_add_u32 s0, s4, s0
	s_addc_u32 s1, s5, s1
	v_writelane_b32 v251, s0, 47
	s_nop 1
	v_writelane_b32 v251, s1, 48
	s_lshl_b32 s0, s6, 4
	v_writelane_b32 v251, s0, 49
	s_lshl_b32 s0, s6, 9
	v_writelane_b32 v251, s0, 50
	s_lshl_b32 s0, s6, 3
	v_writelane_b32 v251, s0, 51
	s_lshl_b32 s0, s6, 11
	v_writelane_b32 v251, s0, 52
	s_add_u32 s0, s4, 0xdc5cc00
	v_writelane_b32 v251, s0, 53
	s_addc_u32 s0, s5, 0
	v_writelane_b32 v251, s0, 54
	s_add_u32 s0, s4, 0xed7cc00
	v_writelane_b32 v251, s0, 55
	s_addc_u32 s0, s5, 0
	v_writelane_b32 v251, s0, 56
	s_add_u32 s0, s4, 0x2808400
	v_writelane_b32 v251, s0, 57
	s_addc_u32 s0, s5, 0
	v_writelane_b32 v251, s0, 58
	s_add_u32 s0, s4, 0x27c8400
	v_writelane_b32 v251, s0, 59
	s_addc_u32 s0, s5, 0
	v_writelane_b32 v251, s0, 60
	s_add_u32 s0, s4, 0x27e8400
	v_writelane_b32 v251, s0, 61
	s_addc_u32 s0, s5, 0
	v_writelane_b32 v251, s0, 62
	s_add_u32 s0, s4, 0xba1cc00
	v_writelane_b32 v251, s0, 63
	s_addc_u32 s0, s5, 0
	v_writelane_b32 v252, s0, 0
	s_add_u32 s0, s4, 0x1d68d000
	s_addc_u32 s1, s5, 0
	s_add_u32 s64, s4, 0x1cdc0c00
	v_writelane_b32 v252, s0, 1
	s_addc_u32 s65, s5, 0
	s_nop 0
	v_writelane_b32 v252, s1, 2
	s_add_u32 s0, s4, 0x1c9a0c00
	v_writelane_b32 v252, s0, 3
	s_addc_u32 s0, s5, 0
	v_writelane_b32 v252, s0, 4
	s_add_u32 s0, s4, 0xb148400
	s_addc_u32 s1, s5, 0
	v_writelane_b32 v252, s0, 5
	s_nop 1
	v_writelane_b32 v252, s1, 6
	s_add_u32 s0, s4, 0xb9d8400
	s_addc_u32 s1, s5, 0
	v_writelane_b32 v252, s0, 7
	s_nop 1
	v_writelane_b32 v252, s1, 8
	s_add_u32 s0, s4, 0x1859cc00
	v_writelane_b32 v252, s0, 9
	s_addc_u32 s0, s5, 0
	v_writelane_b32 v252, s0, 10
	s_add_u32 s0, s4, 0x187a0c00
	v_writelane_b32 v252, s0, 11
	s_addc_u32 s0, s5, 0
	v_writelane_b32 v252, s0, 12
	s_add_u32 s0, s4, 0x1655cc00
	v_writelane_b32 v252, s0, 13
	s_addc_u32 s0, s5, 0
	v_writelane_b32 v252, s0, 14
	s_add_u32 s0, s4, 0x1d791000
	v_writelane_b32 v252, s0, 15
	s_addc_u32 s0, s5, 0
	v_writelane_b32 v252, s0, 16
	v_readlane_b32 s0, v251, 22
	s_add_u32 s2, s0, s2
	v_readlane_b32 s0, v251, 23
	s_addc_u32 s3, s0, s3
	v_writelane_b32 v252, s2, 17
	s_nop 1
	v_writelane_b32 v252, s3, 18
	v_writelane_b32 v252, s64, 19
	s_nop 1
	v_writelane_b32 v252, s65, 20
	s_and_saveexec_b64 s[0:1], s[96:97]
	v_mov_b32_e32 v131, 1
	s_or_b64 exec, exec, s[0:1]
	s_branch .LBB0_1993

; DI int pop_block(int* ctr, int*) {
;   __syncthreads();
;   if (threadIdx.x == 0) sh_item = atomicAdd(ctr, 1);
;   __syncthreads();
;   return __builtin_amdgcn_readfirstlane(sh_item);
; DI void phase_b1(const Params& p, int layer, char*, int*) {
;   int* ctr = (int*)(p.ws + W_CTR) + layer * 4 + 0;
;   for (;;) {
;     int it = pop_block(ctr, nullptr);
;     if (it >= N_SEL + N_LRU1 + N_POOL + N_KMAX) break;
.LBB0_1993:
	s_barrier
	s_and_saveexec_b64 s[0:1], s[96:97]
	s_cbranch_execz .LBB0_1997
	v_readfirstlane_b32 s4, v131
	s_cmp_lg_u32 s4, 0
	s_cbranch_scc1 .Lfp_b
	v_mov_b32_e32 v1, 1
	v_readlane_b32 s4, v251, 47
	v_readlane_b32 s5, v251, 48
	s_nop 4
	global_atomic_add v1, v129, v1, s[4:5] sc0
	s_waitcnt vmcnt(0)
	v_add_u32_e32 v1, 0x200, v1
	s_branch .Lfp_bm
.Lfp_b:
	v_mov_b32_e32 v131, 0
	v_readlane_b32 s4, v249, 54
	s_waitcnt vmcnt(0)
	s_nop 1
	v_mov_b32_e32 v1, s4
.Lfp_bm:
	v_subrev_u32_e32 v0, 0xd10, v1
	v_add_u32_e32 v2, 0x210, v0
	v_subrev_u32_e32 v3, 64, v0
	v_cmp_gt_u32_e32 vcc, 0x230, v0
	s_nop 1
	v_cndmask_b32_e32 v2, v3, v2, vcc
	v_cmp_gt_u32_e32 vcc, 0x1f0, v0
	s_nop 1
	v_cndmask_b32_e32 v2, v2, v0, vcc
	v_cmp_gt_u32_e32 vcc, 0x440, v0
	s_nop 1
	v_cndmask_b32_e32 v2, v0, v2, vcc
	v_add_u32_e32 v3, 0x444, v1
	v_cmp_gt_u32_e32 vcc, 0xd10, v1
	s_nop 1
	v_cndmask_b32_e32 v2, v2, v3, vcc
	v_cmp_gt_u32_e32 vcc, 0x1154, v1
	s_nop 1
	v_cndmask_b32_e32 v1, v1, v2, vcc
	ds_write_b32 v129, v1 offset:32

; DI void phase_b2(const Params& p, int layer, char*, int*) {
;   int* ctr = (int*)(p.ws + W_CTR) + layer * 4 + 1;
;   for (;;) {
;     int it = pop_block(ctr, nullptr);
;     if (it >= N_LRU2) break;
.LBB0_4486:
	s_movk_i32 s89, 0x80
	s_or_b64 exec, exec, s[0:1]
	s_waitcnt lgkmcnt(0)
	s_barrier
	s_mov_b32 s36, 0
	s_ashr_i32 s37, s36, 31
	v_readlane_b32 s0, v249, 0
	v_readlane_b32 s1, v249, 1
	s_add_u32 s48, s0, s36
	v_readlane_b32 s4, v249, 38
	v_readlane_b32 s2, v249, 2
	s_addc_u32 s49, s1, s37
	s_lshl_b64 s[0:1], s[36:37], 2
	v_readlane_b32 s18, v249, 52
	v_readlane_b32 s19, v249, 53
	s_add_u32 s50, s18, s0
	s_mov_b32 s2, s20
	s_addc_u32 s51, s19, s1
	s_lshl_b32 s40, s2, 2
	s_ashr_i32 s41, s40, 31
	s_lshl_b64 s[0:1], s[40:41], 2
	s_add_u32 s38, s48, s0
	s_addc_u32 s39, s49, s1
	s_lshl_b32 s41, s2, 3
	s_lshl_b32 s52, s2, 9
	s_lshl_b32 s53, s2, 11
	s_lshl_b32 s54, s2, 4
	s_add_u32 s55, s48, 0xcb3cc00
	s_addc_u32 s56, s49, 0
	s_add_u32 s57, s48, 0x27c8400
	s_addc_u32 s58, s49, 0
	s_add_u32 s59, s48, 0x27e8400
	s_addc_u32 s60, s49, 0
	s_add_u32 s61, s48, 0xba1cc00
	s_addc_u32 s62, s49, 0
	v_readlane_b32 s0, v251, 24
	s_add_u32 s63, s0, s36
	v_readlane_b32 s0, v251, 25
	s_addc_u32 s88, s0, s37
	v_readlane_b32 s3, v249, 3
	v_readlane_b32 s5, v249, 39
	v_readlane_b32 s6, v249, 40
	v_readlane_b32 s7, v249, 41
	v_readlane_b32 s8, v249, 42
	v_readlane_b32 s9, v249, 43
	v_readlane_b32 s10, v249, 44
	v_readlane_b32 s11, v249, 45
	v_readlane_b32 s12, v249, 46
	v_readlane_b32 s13, v249, 47
	v_readlane_b32 s14, v249, 48
	v_readlane_b32 s15, v249, 49
	v_readlane_b32 s16, v249, 50
	v_readlane_b32 s17, v249, 51
	s_and_saveexec_b64 s[0:1], s[96:97]
	v_mov_b32_e32 v131, 1
	s_or_b64 exec, exec, s[0:1]
	s_branch .LBB0_4489

; DI int pop_block(int* ctr, int*) {
;   __syncthreads();
;   if (threadIdx.x == 0) sh_item = atomicAdd(ctr, 1);
;   __syncthreads();
;   return __builtin_amdgcn_readfirstlane(sh_item);
; DI void phase_b2(const Params& p, int layer, char*, int*) {
;   int* ctr = (int*)(p.ws + W_CTR) + layer * 4 + 1;
;   for (;;) {
;     int it = pop_block(ctr, nullptr);
;     if (it >= N_LRU2) break;
.LBB0_4489:
	s_barrier
	s_and_saveexec_b64 s[0:1], s[96:97]
	s_cbranch_execz .LBB0_4493
	v_readfirstlane_b32 s4, v131
	s_cmp_lg_u32 s4, 0
	s_cbranch_scc1 .Lfp_l
	v_mov_b32_e32 v1, 1
	global_atomic_add v1, v129, v1, s[38:39] offset:4 sc0
	s_waitcnt vmcnt(0)
	v_add_u32_e32 v1, 0x200, v1
	s_branch .Lfp_lm
